# FFN-up GEMM K-loop: removed compiler-inserted vmcnt(0) drain at loop head
# baseline (speedup 1.0000x reference)
; #define PG8_STAGE(bufoff, gbase, voff) do { _Pragma("unroll") for (int _i = 0; _i < 2; ++_i) \
;         __builtin_amdgcn_global_load_lds((const unsigned*)((const char*)(gbase) + (voff)[_i]), (PG8_LAS unsigned*)(lds + (bufoff) + ldsw + _i * 8192), 16, 0, 0); } while (0)
; #define PG8_LDA(dst, b, h) do { _Pragma("unroll") for (int m = 0; m < 4; ++m) _Pragma("unroll") for (int k = 0; k < 2; ++k) dst[m][k] = *(const PG8_LAS bf16x8*)(lds + PG8_SA(b, h) + aoff + m * 2048 + k * 1024); } while (0)
; #define PG8_LDB(dst, b, h) do { _Pragma("unroll") for (int n = 0; n < 2; ++n) _Pragma("unroll") for (int k = 0; k < 2; ++k) dst[n][k] = *(const PG8_LAS bf16x8*)(lds + PG8_SB(b, h) + boff + n * 2048 + k * 1024); } while (0)
; #define PG8_MMA(ai, bj, At, Bt) do { __builtin_amdgcn_s_setprio(1); _Pragma("unroll") for (int m = 0; m < 4; ++m) _Pragma("unroll") for (int n = 0; n < 2; ++n) _Pragma("unroll") for (int k = 0; k < 2; ++k) \
;         acc[ai][bj][m][n] = __builtin_amdgcn_mfma_f32_16x16x32_bf16(Bt[n][k], At[m][k], acc[ai][bj][m][n], 0, 0, 0); __builtin_amdgcn_s_setprio(0); } while (0)
; #define PG8_WAIT_V(n) asm volatile("s_waitcnt vmcnt(" #n ")" ::: "memory")
; #define PG8_WAIT_L(n) asm volatile("s_waitcnt lgkmcnt(" #n ")" ::: "memory")
; #define PG8_BAR __builtin_amdgcn_s_barrier()
; #define PG8_SCHED __builtin_amdgcn_sched_barrier(0)
; template <class Epi, class Sched, bool ALIGN_EPI = false, bool SP2 = false, bool AROWS128 = false>
; __device__ __forceinline__ void gemm_phase(PG8_LAS unsigned char* lds, const Gemm g, const Sched& S, const Epi& E) {
;     ...
;             PG8_LDB(B0, 0, 0); PG8_LDB(B1, 0, 1); PG8_SCHED; PG8_LDA(At, 0, 0); PG8_STAGE(PG8_SA(1, 1), a1 + hstepA, voffA);
;             PG8_WAIT_V(8); PG8_WAIT_L(0); PG8_BAR; PG8_MMA(0, 0, At, B0); PG8_MMA(0, 1, At, B1); PG8_BAR; PG8_SCHED;
;             PG8_LDA(At, 0, 1); PG8_STAGE(PG8_SB(0, 0), b2, voffB); PG8_STAGE(PG8_SB(0, 1), b2 + hstep, voffB); PG8_STAGE(PG8_SA(0, 0), a2, voffA);
;             PG8_WAIT_V(8); PG8_WAIT_L(0); PG8_BAR; PG8_MMA(1, 0, At, B0); PG8_MMA(1, 1, At, B1); PG8_BAR; PG8_SCHED;
.LBB0_626:
	ds_read_b128 v[72:75], v207
	ds_read_b128 v[76:79], v207 offset:1024
	ds_read_b128 v[80:83], v207 offset:2048
	ds_read_b128 v[84:87], v207 offset:3072
	ds_read_b128 v[88:91], v208
	ds_read_b128 v[92:95], v208 offset:1024
	ds_read_b128 v[96:99], v208 offset:2048
	ds_read_b128 v[100:103], v208 offset:3072
	s_add_u32 s20, s18, 0xfffe0080
	s_addc_u32 s21, s19, -1
	s_cmp_eq_u32 s73, 12
	s_cselect_b32 s81, s17, s21
	s_cselect_b32 s80, s33, s20
	s_cselect_b32 s21, s53, s72
	s_cselect_b32 s20, s55, s65
	v_lshl_add_u64 v[220:221], s[18:19], 0, v[168:169]
	s_add_i32 m0, s84, 0xc000
	ds_read_b128 v[176:179], v209
	ds_read_b128 v[180:183], v209 offset:1024
	ds_read_b128 v[184:187], v209 offset:2048
	ds_read_b128 v[188:191], v209 offset:3072
	ds_read_b128 v[192:195], v209 offset:4096
	ds_read_b128 v[196:199], v209 offset:5120
	ds_read_b128 v[212:215], v209 offset:6144
	ds_read_b128 v[216:219], v209 offset:7168
	global_load_lds_dwordx4 v[220:221], off
	v_lshl_add_u64 v[220:221], s[18:19], 0, v[170:171]
	s_add_i32 m0, s84, 0xe000
	s_nop 0
	global_load_lds_dwordx4 v[220:221], off
	s_waitcnt vmcnt(8)
	s_waitcnt lgkmcnt(0)
	s_barrier
	s_setprio 1
	s_waitcnt lgkmcnt(0)
	v_mfma_f32_16x16x32_bf16 v[36:39], v[72:75], v[176:179], v[36:39]
	v_mfma_f32_16x16x32_bf16 v[28:31], v[80:83], v[176:179], v[28:31]
	v_mfma_f32_16x16x32_bf16 v[140:143], v[72:75], v[184:187], v[140:143]
	v_mfma_f32_16x16x32_bf16 v[136:139], v[80:83], v[184:187], v[136:139]
	v_mfma_f32_16x16x32_bf16 v[124:127], v[72:75], v[192:195], v[124:127]
	v_mfma_f32_16x16x32_bf16 v[120:123], v[80:83], v[192:195], v[120:123]
	v_mfma_f32_16x16x32_bf16 v[108:111], v[72:75], v[212:215], v[108:111]
	v_mfma_f32_16x16x32_bf16 v[104:107], v[80:83], v[212:215], v[104:107]
	v_mfma_f32_16x16x32_bf16 v[36:39], v[76:79], v[180:183], v[36:39]
	v_mfma_f32_16x16x32_bf16 v[28:31], v[84:87], v[180:183], v[28:31]
	v_mfma_f32_16x16x32_bf16 v[140:143], v[76:79], v[188:191], v[140:143]
	v_mfma_f32_16x16x32_bf16 v[136:139], v[84:87], v[188:191], v[136:139]
	v_mfma_f32_16x16x32_bf16 v[124:127], v[76:79], v[196:199], v[124:127]
	v_mfma_f32_16x16x32_bf16 v[120:123], v[84:87], v[196:199], v[120:123]
	v_mfma_f32_16x16x32_bf16 v[108:111], v[76:79], v[216:219], v[108:111]
	v_mfma_f32_16x16x32_bf16 v[104:107], v[84:87], v[216:219], v[104:107]
	s_setprio 0
	s_setprio 1
	v_mfma_f32_16x16x32_bf16 v[156:159], v[88:91], v[176:179], v[156:159]
	v_mfma_f32_16x16x32_bf16 v[152:155], v[96:99], v[176:179], v[152:155]
	v_mfma_f32_16x16x32_bf16 v[148:151], v[88:91], v[184:187], v[148:151]
	v_mfma_f32_16x16x32_bf16 v[144:147], v[96:99], v[184:187], v[144:147]
	v_mfma_f32_16x16x32_bf16 v[132:135], v[88:91], v[192:195], v[132:135]
	v_mfma_f32_16x16x32_bf16 v[128:131], v[96:99], v[192:195], v[128:131]
	v_mfma_f32_16x16x32_bf16 v[116:119], v[88:91], v[212:215], v[116:119]
	v_mfma_f32_16x16x32_bf16 v[112:115], v[96:99], v[212:215], v[112:115]
	v_mfma_f32_16x16x32_bf16 v[156:159], v[92:95], v[180:183], v[156:159]
	v_mfma_f32_16x16x32_bf16 v[152:155], v[100:103], v[180:183], v[152:155]
	v_mfma_f32_16x16x32_bf16 v[148:151], v[92:95], v[188:191], v[148:151]
	v_mfma_f32_16x16x32_bf16 v[144:147], v[100:103], v[188:191], v[144:147]
	v_mfma_f32_16x16x32_bf16 v[132:135], v[92:95], v[196:199], v[132:135]
	v_mfma_f32_16x16x32_bf16 v[128:131], v[100:103], v[196:199], v[128:131]
	v_mfma_f32_16x16x32_bf16 v[116:119], v[92:95], v[216:219], v[116:119]
	v_mfma_f32_16x16x32_bf16 v[112:115], v[100:103], v[216:219], v[112:115]
	s_setprio 0
	s_barrier
	s_add_i32 s76, s3, s35
	v_lshl_add_u64 v[220:221], s[20:21], 0, v[162:163]
	s_mov_b32 m0, s76
	ds_read_b128 v[176:179], v209 offset:16384
	ds_read_b128 v[180:183], v209 offset:17408
	ds_read_b128 v[184:187], v209 offset:18432
	ds_read_b128 v[188:191], v209 offset:19456
	ds_read_b128 v[192:195], v209 offset:20480
	ds_read_b128 v[196:199], v209 offset:21504
	ds_read_b128 v[212:215], v209 offset:22528
	ds_read_b128 v[216:219], v209 offset:23552
	global_load_lds_dwordx4 v[220:221], off
	s_add_i32 m0, s76, 0x2000
	s_add_u32 s76, s20, 0x40000
	v_lshl_add_u64 v[222:223], s[20:21], 0, v[166:167]
	s_addc_u32 s77, s21, 0
	s_add_i32 s82, s95, s35
	global_load_lds_dwordx4 v[222:223], off
	v_lshl_add_u64 v[224:225], s[76:77], 0, v[162:163]
	s_mov_b32 m0, s82
	v_lshl_add_u64 v[226:227], s[80:81], 0, v[164:165]
	global_load_lds_dwordx4 v[224:225], off
	v_lshl_add_u64 v[224:225], s[76:77], 0, v[166:167]
	s_add_i32 m0, s82, 0x2000
	s_nop 0
	global_load_lds_dwordx4 v[224:225], off
	v_lshl_add_u64 v[224:225], s[80:81], 0, v[160:161]
	s_mov_b32 m0, s84
	s_nop 0
	global_load_lds_dwordx4 v[224:225], off
	s_mov_b32 m0, s85
	s_nop 0
	global_load_lds_dwordx4 v[226:227], off
	s_waitcnt vmcnt(8)
	s_waitcnt lgkmcnt(0)
	s_barrier
; #define PG8_STAGE(bufoff, gbase, voff) do { _Pragma("unroll") for (int _i = 0; _i < 2; ++_i) \
;         __builtin_amdgcn_global_load_lds((const unsigned*)((const char*)(gbase) + (voff)[_i]), (PG8_LAS unsigned*)(lds + (bufoff) + ldsw + _i * 8192), 16, 0, 0); } while (0)
; #define PG8_LDA(dst, b, h) do { _Pragma("unroll") for (int m = 0; m < 4; ++m) _Pragma("unroll") for (int k = 0; k < 2; ++k) dst[m][k] = *(const PG8_LAS bf16x8*)(lds + PG8_SA(b, h) + aoff + m * 2048 + k * 1024); } while (0)
; #define PG8_LDB(dst, b, h) do { _Pragma("unroll") for (int n = 0; n < 2; ++n) _Pragma("unroll") for (int k = 0; k < 2; ++k) dst[n][k] = *(const PG8_LAS bf16x8*)(lds + PG8_SB(b, h) + boff + n * 2048 + k * 1024); } while (0)
; #define PG8_MMA(ai, bj, At, Bt) do { __builtin_amdgcn_s_setprio(1); _Pragma("unroll") for (int m = 0; m < 4; ++m) _Pragma("unroll") for (int n = 0; n < 2; ++n) _Pragma("unroll") for (int k = 0; k < 2; ++k) \
;         acc[ai][bj][m][n] = __builtin_amdgcn_mfma_f32_16x16x32_bf16(Bt[n][k], At[m][k], acc[ai][bj][m][n], 0, 0, 0); __builtin_amdgcn_s_setprio(0); } while (0)
; #define PG8_WAIT_V(n) asm volatile("s_waitcnt vmcnt(" #n ")" ::: "memory")
; #define PG8_WAIT_L(n) asm volatile("s_waitcnt lgkmcnt(" #n ")" ::: "memory")
; #define PG8_BAR __builtin_amdgcn_s_barrier()
; #define PG8_SCHED __builtin_amdgcn_sched_barrier(0)
; template <class Epi, class Sched, bool ALIGN_EPI = false, bool SP2 = false, bool AROWS128 = false>
; __device__ __forceinline__ void gemm_phase(PG8_LAS unsigned char* lds, const Gemm g, const Sched& S, const Epi& E) {
;     ...
;             PG8_WAIT_V(8); PG8_WAIT_L(0); PG8_BAR; PG8_MMA(1, 0, At, B0); PG8_MMA(1, 1, At, B1); PG8_BAR; PG8_SCHED;
;             PG8_LDB(B0, 1, 0); PG8_LDB(B1, 1, 1); PG8_SCHED; PG8_LDA(At, 1, 0); PG8_STAGE(PG8_SA(0, 1), a2 + hstepA, voffA);
;             PG8_WAIT_V(8); PG8_WAIT_L(0); PG8_BAR; PG8_MMA(0, 0, At, B0); PG8_MMA(0, 1, At, B1); PG8_BAR; PG8_SCHED;
	s_setprio 1
	s_waitcnt lgkmcnt(0)
	v_mfma_f32_16x16x32_bf16 v[60:63], v[72:75], v[176:179], v[60:63]
	v_mfma_f32_16x16x32_bf16 v[56:59], v[80:83], v[176:179], v[56:59]
	v_mfma_f32_16x16x32_bf16 v[44:47], v[72:75], v[184:187], v[44:47]
	v_mfma_f32_16x16x32_bf16 v[40:43], v[80:83], v[184:187], v[40:43]
	v_mfma_f32_16x16x32_bf16 v[20:23], v[72:75], v[192:195], v[20:23]
	v_mfma_f32_16x16x32_bf16 v[16:19], v[80:83], v[192:195], v[16:19]
	v_mfma_f32_16x16x32_bf16 v[12:15], v[72:75], v[212:215], v[12:15]
	v_mfma_f32_16x16x32_bf16 v[8:11], v[80:83], v[212:215], v[8:11]
	v_mfma_f32_16x16x32_bf16 v[60:63], v[76:79], v[180:183], v[60:63]
	v_mfma_f32_16x16x32_bf16 v[56:59], v[84:87], v[180:183], v[56:59]
	v_mfma_f32_16x16x32_bf16 v[44:47], v[76:79], v[188:191], v[44:47]
	v_mfma_f32_16x16x32_bf16 v[40:43], v[84:87], v[188:191], v[40:43]
	v_mfma_f32_16x16x32_bf16 v[20:23], v[76:79], v[196:199], v[20:23]
	v_mfma_f32_16x16x32_bf16 v[16:19], v[84:87], v[196:199], v[16:19]
	v_mfma_f32_16x16x32_bf16 v[12:15], v[76:79], v[216:219], v[12:15]
	v_mfma_f32_16x16x32_bf16 v[8:11], v[84:87], v[216:219], v[8:11]
	s_setprio 0
	s_setprio 1
	v_mfma_f32_16x16x32_bf16 v[68:71], v[88:91], v[176:179], v[68:71]
	v_mfma_f32_16x16x32_bf16 v[64:67], v[96:99], v[176:179], v[64:67]
	v_mfma_f32_16x16x32_bf16 v[52:55], v[88:91], v[184:187], v[52:55]
	v_mfma_f32_16x16x32_bf16 v[48:51], v[96:99], v[184:187], v[48:51]
	v_mfma_f32_16x16x32_bf16 v[32:35], v[88:91], v[192:195], v[32:35]
	v_mfma_f32_16x16x32_bf16 v[24:27], v[96:99], v[192:195], v[24:27]
	v_mfma_f32_16x16x32_bf16 v[4:7], v[88:91], v[212:215], v[4:7]
	v_mfma_f32_16x16x32_bf16 v[0:3], v[96:99], v[212:215], v[0:3]
	v_mfma_f32_16x16x32_bf16 v[68:71], v[92:95], v[180:183], v[68:71]
	v_mfma_f32_16x16x32_bf16 v[64:67], v[100:103], v[180:183], v[64:67]
	v_mfma_f32_16x16x32_bf16 v[52:55], v[92:95], v[188:191], v[52:55]
	v_mfma_f32_16x16x32_bf16 v[48:51], v[100:103], v[188:191], v[48:51]
	v_mfma_f32_16x16x32_bf16 v[32:35], v[92:95], v[196:199], v[32:35]
	v_mfma_f32_16x16x32_bf16 v[24:27], v[100:103], v[196:199], v[24:27]
	v_mfma_f32_16x16x32_bf16 v[4:7], v[92:95], v[216:219], v[4:7]
	v_mfma_f32_16x16x32_bf16 v[0:3], v[100:103], v[216:219], v[0:3]
	s_setprio 0
	s_barrier
	s_add_i32 s82, 0, 0x18000
	s_add_i32 s83, 0, 0x1c000
	v_add_u32_e32 v84, s82, v200
	v_add_u32_e32 v100, s83, v200
	ds_read_b128 v[72:75], v84
	ds_read_b128 v[76:79], v84 offset:1024
	ds_read_b128 v[80:83], v84 offset:2048
	ds_read_b128 v[84:87], v84 offset:3072
	ds_read_b128 v[88:91], v100
	ds_read_b128 v[92:95], v100 offset:1024
	ds_read_b128 v[96:99], v100 offset:2048
	ds_read_b128 v[100:103], v100 offset:3072
	s_add_u32 s76, s80, 0x20000
	s_addc_u32 s77, s81, 0
	s_mov_b32 m0, s86
	v_lshl_add_u64 v[228:229], s[76:77], 0, v[160:161]
	ds_read_b128 v[176:179], v209 offset:32768
	ds_read_b128 v[180:183], v209 offset:33792
	ds_read_b128 v[184:187], v209 offset:34816
	ds_read_b128 v[188:191], v209 offset:35840
	ds_read_b128 v[192:195], v209 offset:36864
	ds_read_b128 v[196:199], v209 offset:37888
	ds_read_b128 v[212:215], v209 offset:38912
	ds_read_b128 v[216:219], v209 offset:39936
	global_load_lds_dwordx4 v[228:229], off
	v_lshl_add_u64 v[228:229], s[76:77], 0, v[164:165]
	s_mov_b32 m0, s87
	s_nop 0
	global_load_lds_dwordx4 v[228:229], off
	s_waitcnt vmcnt(8)
	s_waitcnt lgkmcnt(0)
	s_barrier
	s_setprio 1
	s_waitcnt lgkmcnt(0)
	v_mfma_f32_16x16x32_bf16 v[36:39], v[72:75], v[176:179], v[36:39]
	v_mfma_f32_16x16x32_bf16 v[28:31], v[80:83], v[176:179], v[28:31]
	v_mfma_f32_16x16x32_bf16 v[140:143], v[72:75], v[184:187], v[140:143]
	v_mfma_f32_16x16x32_bf16 v[136:139], v[80:83], v[184:187], v[136:139]
	v_mfma_f32_16x16x32_bf16 v[124:127], v[72:75], v[192:195], v[124:127]
	v_mfma_f32_16x16x32_bf16 v[120:123], v[80:83], v[192:195], v[120:123]
	v_mfma_f32_16x16x32_bf16 v[108:111], v[72:75], v[212:215], v[108:111]
	v_mfma_f32_16x16x32_bf16 v[104:107], v[80:83], v[212:215], v[104:107]
	v_mfma_f32_16x16x32_bf16 v[36:39], v[76:79], v[180:183], v[36:39]
	v_mfma_f32_16x16x32_bf16 v[28:31], v[84:87], v[180:183], v[28:31]
	v_mfma_f32_16x16x32_bf16 v[140:143], v[76:79], v[188:191], v[140:143]
	v_mfma_f32_16x16x32_bf16 v[136:139], v[84:87], v[188:191], v[136:139]
	v_mfma_f32_16x16x32_bf16 v[124:127], v[76:79], v[196:199], v[124:127]
	v_mfma_f32_16x16x32_bf16 v[120:123], v[84:87], v[196:199], v[120:123]
	v_mfma_f32_16x16x32_bf16 v[108:111], v[76:79], v[216:219], v[108:111]
	v_mfma_f32_16x16x32_bf16 v[104:107], v[84:87], v[216:219], v[104:107]
	s_setprio 0
	s_setprio 1
	v_mfma_f32_16x16x32_bf16 v[156:159], v[88:91], v[176:179], v[156:159]
	v_mfma_f32_16x16x32_bf16 v[152:155], v[96:99], v[176:179], v[152:155]
	v_mfma_f32_16x16x32_bf16 v[148:151], v[88:91], v[184:187], v[148:151]
	v_mfma_f32_16x16x32_bf16 v[144:147], v[96:99], v[184:187], v[144:147]
	v_mfma_f32_16x16x32_bf16 v[132:135], v[88:91], v[192:195], v[132:135]
	v_mfma_f32_16x16x32_bf16 v[128:131], v[96:99], v[192:195], v[128:131]
	v_mfma_f32_16x16x32_bf16 v[116:119], v[88:91], v[212:215], v[116:119]
	v_mfma_f32_16x16x32_bf16 v[112:115], v[96:99], v[212:215], v[112:115]
	v_mfma_f32_16x16x32_bf16 v[156:159], v[92:95], v[180:183], v[156:159]
	v_mfma_f32_16x16x32_bf16 v[152:155], v[100:103], v[180:183], v[152:155]
	v_mfma_f32_16x16x32_bf16 v[148:151], v[92:95], v[188:191], v[148:151]
	v_mfma_f32_16x16x32_bf16 v[144:147], v[100:103], v[188:191], v[144:147]
	v_mfma_f32_16x16x32_bf16 v[132:135], v[92:95], v[196:199], v[132:135]
	v_mfma_f32_16x16x32_bf16 v[128:131], v[100:103], v[196:199], v[128:131]
	v_mfma_f32_16x16x32_bf16 v[116:119], v[92:95], v[216:219], v[116:119]
	v_mfma_f32_16x16x32_bf16 v[112:115], v[100:103], v[216:219], v[112:115]
	s_setprio 0
	s_barrier
; #define PG8_STAGE(bufoff, gbase, voff) do { _Pragma("unroll") for (int _i = 0; _i < 2; ++_i) \
;         __builtin_amdgcn_global_load_lds((const unsigned*)((const char*)(gbase) + (voff)[_i]), (PG8_LAS unsigned*)(lds + (bufoff) + ldsw + _i * 8192), 16, 0, 0); } while (0)
; #define PG8_LDA(dst, b, h) do { _Pragma("unroll") for (int m = 0; m < 4; ++m) _Pragma("unroll") for (int k = 0; k < 2; ++k) dst[m][k] = *(const PG8_LAS bf16x8*)(lds + PG8_SA(b, h) + aoff + m * 2048 + k * 1024); } while (0)
; #define PG8_MMA(ai, bj, At, Bt) do { __builtin_amdgcn_s_setprio(1); _Pragma("unroll") for (int m = 0; m < 4; ++m) _Pragma("unroll") for (int n = 0; n < 2; ++n) _Pragma("unroll") for (int k = 0; k < 2; ++k) \
;         acc[ai][bj][m][n] = __builtin_amdgcn_mfma_f32_16x16x32_bf16(Bt[n][k], At[m][k], acc[ai][bj][m][n], 0, 0, 0); __builtin_amdgcn_s_setprio(0); } while (0)
; #define PG8_WAIT_V(n) asm volatile("s_waitcnt vmcnt(" #n ")" ::: "memory")
; #define PG8_WAIT_L(n) asm volatile("s_waitcnt lgkmcnt(" #n ")" ::: "memory")
; #define PG8_BAR __builtin_amdgcn_s_barrier()
; #define PG8_SCHED __builtin_amdgcn_sched_barrier(0)
; template <class Epi, class Sched, bool ALIGN_EPI = false, bool SP2 = false, bool AROWS128 = false>
; __device__ __forceinline__ void gemm_phase(PG8_LAS unsigned char* lds, const Gemm g, const Sched& S, const Epi& E) {
;     ...
;         for (int t = 0; t < nt; t += 2) {
;     ...
;             PG8_LDA(At, 1, 1); PG8_STAGE(PG8_SB(1, 0), b3, voffB); PG8_STAGE(PG8_SB(1, 1), b3 + hstep, voffB); PG8_STAGE(PG8_SA(1, 0), a3, voffA);
;             PG8_WAIT_V(8); PG8_WAIT_L(0); PG8_BAR; PG8_MMA(1, 0, At, B0); PG8_MMA(1, 1, At, B1); PG8_BAR; PG8_SCHED;
;     ...
;         if constexpr (ALIGN_EPI) { if (wr == 0) PG8_BAR; }
	s_add_i32 s76, s82, s35
	v_lshl_add_u64 v[220:221], v[220:221], 0, s[26:27]
	s_mov_b32 m0, s76
	ds_read_b128 v[176:179], v209 offset:49152
	ds_read_b128 v[180:183], v209 offset:50176
	ds_read_b128 v[184:187], v209 offset:51200
	ds_read_b128 v[188:191], v209 offset:52224
	ds_read_b128 v[192:195], v209 offset:53248
	ds_read_b128 v[196:199], v209 offset:54272
	ds_read_b128 v[212:215], v209 offset:55296
	ds_read_b128 v[216:219], v209 offset:56320
	global_load_lds_dwordx4 v[220:221], off
	s_add_i32 m0, s76, 0x2000
	s_add_u32 s20, s20, 0x40080
	v_lshl_add_u64 v[220:221], v[222:223], 0, s[26:27]
	s_addc_u32 s21, s21, 0
	s_add_i32 s76, s83, s35
	global_load_lds_dwordx4 v[220:221], off
	v_lshl_add_u64 v[220:221], s[20:21], 0, v[162:163]
	s_mov_b32 m0, s76
	s_nop 0
	global_load_lds_dwordx4 v[220:221], off
	v_lshl_add_u64 v[220:221], s[20:21], 0, v[166:167]
	s_add_i32 m0, s76, 0x2000
	s_nop 0
	global_load_lds_dwordx4 v[220:221], off
	v_lshl_add_u64 v[220:221], v[224:225], 0, s[26:27]
	s_mov_b32 m0, s89
	s_nop 0
	global_load_lds_dwordx4 v[220:221], off
	v_lshl_add_u64 v[220:221], v[226:227], 0, s[26:27]
	s_mov_b32 m0, s90
	s_nop 0
	global_load_lds_dwordx4 v[220:221], off
	s_waitcnt vmcnt(8)
	s_waitcnt lgkmcnt(0)
	s_barrier
	s_setprio 1
	s_waitcnt lgkmcnt(0)
	v_mfma_f32_16x16x32_bf16 v[60:63], v[72:75], v[176:179], v[60:63]
	v_mfma_f32_16x16x32_bf16 v[56:59], v[80:83], v[176:179], v[56:59]
	v_mfma_f32_16x16x32_bf16 v[44:47], v[72:75], v[184:187], v[44:47]
	v_mfma_f32_16x16x32_bf16 v[40:43], v[80:83], v[184:187], v[40:43]
	v_mfma_f32_16x16x32_bf16 v[20:23], v[72:75], v[192:195], v[20:23]
	v_mfma_f32_16x16x32_bf16 v[16:19], v[80:83], v[192:195], v[16:19]
	v_mfma_f32_16x16x32_bf16 v[12:15], v[72:75], v[212:215], v[12:15]
	v_mfma_f32_16x16x32_bf16 v[8:11], v[80:83], v[212:215], v[8:11]
	v_mfma_f32_16x16x32_bf16 v[60:63], v[76:79], v[180:183], v[60:63]
	v_mfma_f32_16x16x32_bf16 v[56:59], v[84:87], v[180:183], v[56:59]
	v_mfma_f32_16x16x32_bf16 v[44:47], v[76:79], v[188:191], v[44:47]
	v_mfma_f32_16x16x32_bf16 v[40:43], v[84:87], v[188:191], v[40:43]
	v_mfma_f32_16x16x32_bf16 v[20:23], v[76:79], v[196:199], v[20:23]
	v_mfma_f32_16x16x32_bf16 v[16:19], v[84:87], v[196:199], v[16:19]
	v_mfma_f32_16x16x32_bf16 v[12:15], v[76:79], v[216:219], v[12:15]
	v_mfma_f32_16x16x32_bf16 v[8:11], v[84:87], v[216:219], v[8:11]
	s_setprio 0
	s_setprio 1
	v_mfma_f32_16x16x32_bf16 v[68:71], v[88:91], v[176:179], v[68:71]
	v_mfma_f32_16x16x32_bf16 v[64:67], v[96:99], v[176:179], v[64:67]
	v_mfma_f32_16x16x32_bf16 v[52:55], v[88:91], v[184:187], v[52:55]
	v_mfma_f32_16x16x32_bf16 v[48:51], v[96:99], v[184:187], v[48:51]
	v_mfma_f32_16x16x32_bf16 v[32:35], v[88:91], v[192:195], v[32:35]
	v_mfma_f32_16x16x32_bf16 v[24:27], v[96:99], v[192:195], v[24:27]
	v_mfma_f32_16x16x32_bf16 v[4:7], v[88:91], v[212:215], v[4:7]
	v_mfma_f32_16x16x32_bf16 v[0:3], v[96:99], v[212:215], v[0:3]
	v_mfma_f32_16x16x32_bf16 v[68:71], v[92:95], v[180:183], v[68:71]
	v_mfma_f32_16x16x32_bf16 v[64:67], v[100:103], v[180:183], v[64:67]
	v_mfma_f32_16x16x32_bf16 v[52:55], v[92:95], v[188:191], v[52:55]
	v_mfma_f32_16x16x32_bf16 v[48:51], v[100:103], v[188:191], v[48:51]
	v_mfma_f32_16x16x32_bf16 v[32:35], v[92:95], v[196:199], v[32:35]
	v_mfma_f32_16x16x32_bf16 v[24:27], v[100:103], v[196:199], v[24:27]
	v_mfma_f32_16x16x32_bf16 v[4:7], v[92:95], v[216:219], v[4:7]
	v_mfma_f32_16x16x32_bf16 v[0:3], v[100:103], v[216:219], v[0:3]
	s_setprio 0
	s_barrier
	s_add_i32 s73, s73, 2
	s_add_u32 s18, s18, 0x100
	s_addc_u32 s19, s19, 0
	s_add_u32 s65, s65, 0x100
	s_addc_u32 s72, s72, 0
	s_cmp_gt_u32 s73, 13
	s_cbranch_scc0 .LBB0_626
	s_and_b64 vcc, exec, s[28:29]
	s_cbranch_vccz .LBB0_629
	s_barrier
